# one static s_setprio 1 for the trailing wave half (waves 4-7) at each GEMM phase's unit-loop entry
# speedup vs baseline: 1.0020x; 1.0020x over previous
; #define PG8_STAGE(bufoff, gbase, voff) do { _Pragma("unroll") for (int _i = 0; _i < 2; ++_i) \
;         __builtin_amdgcn_global_load_lds((const unsigned*)((const char*)(gbase) + (voff)[_i]), (PG8_LAS unsigned*)(lds + (bufoff) + ldsw + _i * 8192), 16, 0, 0); } while (0)
; #define PG8_WAIT_V(n) asm volatile("s_waitcnt vmcnt(" #n ")" ::: "memory")
; #define PG8_BAR __builtin_amdgcn_s_barrier()
; template <class Epi, class Sched, bool ALIGN_EPI = false, bool SP2 = false>
; __device__ __forceinline__ void gemm_phase(PG8_LAS unsigned char* lds, const Gemm g, const Sched& S, const Epi& E) {
;     ...
;     const int tid = tid_o, wid = __builtin_amdgcn_readfirstlane(tid >> 6), lane = tid & 63, wr = wid >> 2, wc = wid & 3, fr = lane & 15, fq = lane >> 4;
;     const int K = g.K, nt = K / BK;
;     unsigned voffA[2], voffB[2];
; #pragma unroll
;     for (int i = 0; i < 2; ++i) { int R, C; stage_rc(tid * 16 + i * 8192, R, C); const int Rb = Epi::PERM ? ((R & ~31) + perm32(R & 31)) : R;
;         voffA[i] = (unsigned)(R * g.lda + C) * 2u; voffB[i] = (unsigned)(Rb * g.ldb + C) * 2u; }
;     const size_t kstep = (size_t)(BK * 2);
;     const size_t hA = (size_t)HALF * g.lda * 2, hB = (size_t)HALF * g.ldb * 2;
;     const size_t tA = 2 * hA, tB = 2 * hB, pnA = (size_t)g.a_pn_off * 2;
;     const unsigned ldsw = (unsigned)wid * 1024u;
;     const int aoff = lds_byte(wr * 64 + fr, fq * 8), boff = lds_byte(wc * 32 + fr, fq * 8);
;     ...
;         PG8_STAGE(PG8_SB(1, 0), cB + kstep, voffB); PG8_STAGE(PG8_SA(1, 0), cA + kstep, voffA); PG8_STAGE(PG8_SB(1, 1), cB + hB + kstep, voffB);
;         PG8_WAIT_V(6); PG8_BAR;
.LBB0_184:
	s_add_u32 s14, s0, 0x15800000
	s_waitcnt vmcnt(0)
	v_bfe_u32 v19, v10, 4, 2
	s_addc_u32 s15, s1, 0
	v_and_b32_e32 v18, 15, v10
	v_lshlrev_b32_e32 v20, 3, v19
	v_lshlrev_b32_e32 v19, 4, v19
	s_add_u32 s16, s0, 0x1d800000
	v_lshl_or_b32 v1, s5, 6, v18
	v_lshl_or_b32 v19, v18, 6, v19
	v_lshlrev_b32_e32 v18, 2, v18
	s_mov_b64 s[38:39], 0x80
	s_addc_u32 s17, s1, 0
	s_and_b32 s8, s4, 3
	s_lshl_b32 s4, s5, 13
	v_and_b32_e32 v21, 32, v18
	s_add_i32 m0, s74, 0x18000
	v_lshl_add_u64 v[8:9], v[8:9], 0, s[38:39]
	v_bitop3_b32 v22, v19, s4, v21 bitop3:0xde
	s_lshl_b32 s4, s8, 12
	s_waitcnt vmcnt(2)
	s_barrier
	global_load_lds_dwordx4 v[8:9], off
	v_lshl_add_u64 v[6:7], v[6:7], 0, s[38:39]
	s_add_i32 m0, s74, 0x1a000
	s_add_i32 s81, s74, 0x8000
	s_add_i32 s82, s74, 0xa000
	v_bitop3_b32 v223, v19, s4, v21 bitop3:0xde
	global_load_lds_dwordx4 v[6:7], off
	v_lshl_add_u64 v[4:5], v[4:5], 0, s[38:39]
	s_mov_b32 m0, s81
	s_add_u32 s4, s64, 0x80080
	global_load_lds_dwordx4 v[4:5], off
	v_lshl_add_u64 v[2:3], v[2:3], 0, s[38:39]
	s_mov_b32 m0, s82
	s_addc_u32 s5, s65, 0
	global_load_lds_dwordx4 v[2:3], off
	s_add_i32 m0, s74, 0x1c000
	v_lshl_add_u64 v[2:3], s[4:5], 0, v[196:197]
	global_load_lds_dwordx4 v[2:3], off
	v_lshl_add_u64 v[2:3], s[4:5], 0, v[200:201]
	s_add_i32 m0, s74, 0x1e000
	v_lshrrev_b32_e32 v17, 4, v10
	global_load_lds_dwordx4 v[2:3], off
	v_and_b32_e32 v2, 3, v10
	s_cmpk_lt_u32 s6, 0x100
	v_lshlrev_b32_e32 v3, 1, v2
	v_cmp_gt_u32_e64 s[6:7], 2, v2
	v_bfe_u32 v2, v17, 1, 1
	v_lshl_or_b32 v227, s8, 2, v2
	v_lshlrev_b32_e32 v2, 1, v10
	v_or_b32_e32 v5, v20, v3
	v_and_b32_e32 v228, 32, v2
	v_bitop3_b32 v2, v20, 18, v3 bitop3:0xc8
	v_lshrrev_b32_e32 v3, 2, v10
	s_cselect_b64 s[40:41], -1, 0
	s_lshl_b32 s9, s8, 8
	v_and_b32_e32 v6, 4, v10
	v_and_b32_e32 v3, 4, v3
	v_or3_b32 v5, v21, s9, v5
	v_and_b32_e32 v7, 1, v10
	v_and_or_b32 v3, v18, 40, v3
	v_lshlrev_b32_e32 v6, 1, v6
	v_cmp_eq_u32_e64 s[4:5], 0, v7
	v_or3_b32 v7, v3, v2, s9
	v_lshl_or_b32 v202, v5, 4, v6
	v_lshl_or_b32 v4, s8, 5, v20
	v_lshl_add_u64 v[2:3], s[0:1], 0, v[202:203]
	s_mov_b64 s[8:9], 0xd800000
	v_lshl_or_b32 v202, v7, 4, v6
	v_lshl_add_u64 v[204:205], v[2:3], 0, s[8:9]
	v_lshl_add_u64 v[2:3], s[0:1], 0, v[202:203]
	s_mov_b64 s[8:9], 0x11800000
	v_lshlrev_b32_e32 v202, 2, v4
	v_lshl_add_u64 v[206:207], v[2:3], 0, s[8:9]
	v_lshl_add_u64 v[2:3], s[0:1], 0, v[202:203]
	s_mov_b64 s[42:43], 0x100000
	s_mov_b64 s[8:9], 0x300000
	v_lshl_add_u64 v[208:209], v[2:3], 0, s[42:43]
	v_lshl_add_u64 v[210:211], v[2:3], 0, s[8:9]
	v_lshlrev_b32_e32 v2, 15, v11
	v_and_b32_e32 v2, 0xffff0000, v2
	v_lshl_add_u32 v2, v12, 12, v2
	v_and_b32_e32 v3, 1, v11
	v_lshl_or_b32 v2, v3, 6, v2
	v_lshl_add_u32 v212, v13, 1, v2
	v_lshlrev_b32_e32 v2, 15, v14
	v_and_b32_e32 v2, 0xffff0000, v2
	s_waitcnt vmcnt(6)
	v_lshl_add_u32 v2, v15, 12, v2
	v_and_b32_e32 v3, 1, v14
	v_lshl_or_b32 v2, v3, 6, v2
	s_add_i32 s84, 0, 0x10000
	s_add_i32 s85, 0, 0x14000
	v_or_b32_e32 v224, 0xffffdc00, v4
	v_or_b32_e32 v225, 0xffffe000, v4
	v_or_b32_e32 v226, 0xffffe800, v4
	s_waitcnt lgkmcnt(0)
	s_ashr_i32 s83, s78, 31
	v_mov_b32_e32 v213, v203
	v_lshl_add_u32 v214, v16, 1, v2
	v_mov_b32_e32 v215, v203
	v_mov_b64_e32 v[216:217], 0xd00
	v_mov_b64_e32 v[218:219], 0xcff
	v_add_u32_e32 v229, s84, v223
	v_add_u32_e32 v230, s85, v223
	v_add_u32_e32 v231, 0, v22
	s_mov_b32 s18, 0x58000
	s_mov_b32 s87, 0x80000
	s_mov_b64 s[44:45], 0x90000
	s_mov_b32 s88, 0x90000
	s_mov_b64 s[46:47], 0xa0000
	s_mov_b32 s89, 0xa0000
	s_mov_b64 s[48:49], 0xb0000
	s_mov_b32 s90, 0xb0000
	s_mov_b32 s91, 0x5040100
	s_mov_b32 s92, 0x7060302
	s_mov_b32 s93, 0x9800000
	s_mov_b32 s94, 0xc2fc0000
	s_mov_b32 s95, 0x800000
	s_mov_b32 s50, 0x3d800000
	v_mov_b32_e32 v232, 0x42800000
	v_mov_b32_e32 v233, 0x42000000
	v_not_b32_e32 v234, 63
	s_barrier
	v_readfirstlane_b32 s101, v0
	s_nop 3
	s_lshr_b32 s101, s101, 8
	s_cmp_eq_u32 s101, 1
	s_cbranch_scc0 .Lsp_0
	s_setprio 1

; #define PG8_STAGE(bufoff, gbase, voff) do { _Pragma("unroll") for (int _i = 0; _i < 2; ++_i) \
;         __builtin_amdgcn_global_load_lds((const unsigned*)((const char*)(gbase) + (voff)[_i]), (PG8_LAS unsigned*)(lds + (bufoff) + ldsw + _i * 8192), 16, 0, 0); } while (0)
; #define PG8_WAIT_V(n) asm volatile("s_waitcnt vmcnt(" #n ")" ::: "memory")
; #define PG8_BAR __builtin_amdgcn_s_barrier()
; template <class Epi, class Sched, bool ALIGN_EPI = false, bool SP2 = false>
; __device__ __forceinline__ void gemm_phase(PG8_LAS unsigned char* lds, const Gemm g, const Sched& S, const Epi& E) {
;     ...
;     const int tid = tid_o, wid = __builtin_amdgcn_readfirstlane(tid >> 6), lane = tid & 63, wr = wid >> 2, wc = wid & 3, fr = lane & 15, fq = lane >> 4;
;     const int K = g.K, nt = K / BK;
;     unsigned voffA[2], voffB[2];
; #pragma unroll
;     for (int i = 0; i < 2; ++i) { int R, C; stage_rc(tid * 16 + i * 8192, R, C); const int Rb = Epi::PERM ? ((R & ~31) + perm32(R & 31)) : R;
;         voffA[i] = (unsigned)(R * g.lda + C) * 2u; voffB[i] = (unsigned)(Rb * g.ldb + C) * 2u; }
;     const size_t kstep = (size_t)(BK * 2);
;     const size_t hA = (size_t)HALF * g.lda * 2, hB = (size_t)HALF * g.ldb * 2;
;     const size_t tA = 2 * hA, tB = 2 * hB, pnA = (size_t)g.a_pn_off * 2;
;     const unsigned ldsw = (unsigned)wid * 1024u;
;     const int aoff = lds_byte(wr * 64 + fr, fq * 8), boff = lds_byte(wc * 32 + fr, fq * 8);
;     ...
;         PG8_STAGE(PG8_SB(1, 0), cB + kstep, voffB); PG8_STAGE(PG8_SA(1, 0), cA + kstep, voffA); PG8_STAGE(PG8_SB(1, 1), cB + hB + kstep, voffB);
;         PG8_WAIT_V(6); PG8_BAR;
.LBB0_858:
	s_add_u32 s6, s4, 0xd800000
	s_addc_u32 s7, s5, 0
	s_lshl_b32 s4, s8, 5
	s_mov_b64 s[8:9], 0x80
	s_and_b32 s18, s4, 0x60
	s_add_i32 m0, s41, 0x18000
	v_lshl_add_u64 v[8:9], v[8:9], 0, s[8:9]
	s_lshl_b32 s17, s16, 13
	s_lshl_b32 s19, s18, 7
	s_waitcnt vmcnt(2)
	s_barrier
	global_load_lds_dwordx4 v[8:9], off
	v_lshl_add_u64 v[6:7], v[6:7], 0, s[8:9]
	s_add_i32 m0, s41, 0x1a000
	s_add_i32 s60, s41, 0x8000
	s_add_i32 s61, s41, 0xa000
	global_load_lds_dwordx4 v[6:7], off
	v_lshl_add_u64 v[2:3], v[2:3], 0, s[8:9]
	s_mov_b32 m0, s60
	s_add_u32 s4, s44, 0x40080
	global_load_lds_dwordx4 v[2:3], off
	v_lshl_add_u64 v[2:3], v[4:5], 0, s[8:9]
	s_mov_b32 m0, s61
	s_addc_u32 s5, s45, 0
	global_load_lds_dwordx4 v[2:3], off
	s_add_i32 m0, s41, 0x1c000
	v_lshl_add_u64 v[2:3], s[4:5], 0, v[134:135]
	global_load_lds_dwordx4 v[2:3], off
	v_lshl_add_u64 v[2:3], s[4:5], 0, v[130:131]
	s_add_i32 m0, s41, 0x1e000
	s_cmpk_lt_u32 s15, 0x100
	global_load_lds_dwordx4 v[2:3], off
	v_lshrrev_b32_e32 v3, 1, v11
	v_and_b32_e32 v3, 24, v3
	v_and_b32_e32 v2, 15, v11
	v_lshlrev_b32_e32 v4, 1, v3
	v_lshl_or_b32 v1, s16, 6, v2
	v_lshl_or_b32 v2, v2, 6, v4
	v_lshlrev_b32_e32 v4, 2, v11
	v_and_b32_e32 v4, 32, v4
	v_bitop3_b32 v5, v2, s17, v4 bitop3:0xde
	v_bitop3_b32 v154, v2, s19, v4 bitop3:0xde
	v_lshlrev_b32_e32 v2, 14, v15
	v_and_b32_e32 v2, 0xffff8000, v2
	v_or_b32_e32 v155, s18, v3
	v_lshl_add_u32 v2, v14, 11, v2
	v_and_b32_e32 v3, 1, v15
	v_lshl_or_b32 v2, v3, 6, v2
	v_lshl_add_u32 v138, v16, 1, v2
	v_lshlrev_b32_e32 v2, 14, v10
	v_and_b32_e32 v2, 0xffff8000, v2
	s_waitcnt vmcnt(6)
	v_lshl_add_u32 v2, v12, 11, v2
	v_and_b32_e32 v3, 1, v10
	s_sext_i32_i8 s66, s14
	s_cselect_b64 s[14:15], -1, 0
	v_lshl_or_b32 v2, v3, 6, v2
	s_add_i32 s64, 0, 0x10000
	s_add_i32 s65, 0, 0x14000
	s_mov_b32 s62, 0
	s_waitcnt lgkmcnt(0)
	s_ashr_i32 s63, s50, 31
	v_mov_b32_e32 v139, v135
	v_lshl_add_u32 v140, v13, 1, v2
	v_mov_b32_e32 v141, v135
	v_mov_b64_e32 v[142:143], 0x200
	v_mov_b64_e32 v[144:145], 0x1ff
	v_add_u32_e32 v156, s64, v154
	v_add_u32_e32 v157, s65, v154
	v_add_u32_e32 v158, 0, v5
	s_mov_b64 s[16:17], 0x1000
	s_barrier
	v_readfirstlane_b32 s101, v0
	s_nop 3
	s_lshr_b32 s101, s101, 8
	s_cmp_eq_u32 s101, 1
	s_cbranch_scc0 .Lsp_1
	s_setprio 1

; #define PG8_STAGE(bufoff, gbase, voff) do { _Pragma("unroll") for (int _i = 0; _i < 2; ++_i) \
;         __builtin_amdgcn_global_load_lds((const unsigned*)((const char*)(gbase) + (voff)[_i]), (PG8_LAS unsigned*)(lds + (bufoff) + ldsw + _i * 8192), 16, 0, 0); } while (0)
; #define PG8_WAIT_V(n) asm volatile("s_waitcnt vmcnt(" #n ")" ::: "memory")
; #define PG8_BAR __builtin_amdgcn_s_barrier()
; template <class Epi, class Sched, bool ALIGN_EPI = false, bool SP2 = false>
; __device__ __forceinline__ void gemm_phase(PG8_LAS unsigned char* lds, const Gemm g, const Sched& S, const Epi& E) {
;     ...
;     const int tid = tid_o, wid = __builtin_amdgcn_readfirstlane(tid >> 6), lane = tid & 63, wr = wid >> 2, wc = wid & 3, fr = lane & 15, fq = lane >> 4;
;     const int K = g.K, nt = K / BK;
;     unsigned voffA[2], voffB[2];
; #pragma unroll
;     for (int i = 0; i < 2; ++i) { int R, C; stage_rc(tid * 16 + i * 8192, R, C); const int Rb = Epi::PERM ? ((R & ~31) + perm32(R & 31)) : R;
;         voffA[i] = (unsigned)(R * g.lda + C) * 2u; voffB[i] = (unsigned)(Rb * g.ldb + C) * 2u; }
;     const size_t kstep = (size_t)(BK * 2);
;     const size_t hA = (size_t)HALF * g.lda * 2, hB = (size_t)HALF * g.ldb * 2;
;     const size_t tA = 2 * hA, tB = 2 * hB, pnA = (size_t)g.a_pn_off * 2;
;     const unsigned ldsw = (unsigned)wid * 1024u;
;     const int aoff = lds_byte(wr * 64 + fr, fq * 8), boff = lds_byte(wc * 32 + fr, fq * 8);
;     ...
;         PG8_STAGE(PG8_SB(1, 0), cB + kstep, voffB); PG8_STAGE(PG8_SA(1, 0), cA + kstep, voffA); PG8_STAGE(PG8_SB(1, 1), cB + hB + kstep, voffB);
;         PG8_WAIT_V(6); PG8_BAR;
.LBB0_878:
	s_add_u32 s8, s6, 0xd800000
	s_addc_u32 s9, s7, 0
	s_add_u32 s14, s6, 0x9800000
	s_addc_u32 s15, s7, 0
	s_lshl_b32 s6, s16, 5
	s_mov_b64 s[16:17], 0x80
	s_and_b32 s19, s6, 0x60
	s_add_i32 m0, s43, 0x18000
	v_lshl_add_u64 v[8:9], v[8:9], 0, s[16:17]
	s_lshl_b32 s18, s22, 13
	s_lshl_b32 s23, s19, 7
	s_waitcnt vmcnt(2)
	s_barrier
	global_load_lds_dwordx4 v[8:9], off
	v_lshl_add_u64 v[6:7], v[6:7], 0, s[16:17]
	s_add_i32 m0, s43, 0x1a000
	s_add_i32 s63, s43, 0x8000
	s_add_i32 s64, s43, 0xa000
	global_load_lds_dwordx4 v[6:7], off
	v_lshl_add_u64 v[2:3], v[2:3], 0, s[16:17]
	s_mov_b32 m0, s63
	s_add_u32 s6, s46, 0x80080
	global_load_lds_dwordx4 v[2:3], off
	v_lshl_add_u64 v[2:3], v[4:5], 0, s[16:17]
	s_mov_b32 m0, s64
	s_addc_u32 s7, s47, 0
	global_load_lds_dwordx4 v[2:3], off
	s_add_i32 m0, s43, 0x1c000
	v_lshl_add_u64 v[2:3], s[6:7], 0, v[150:151]
	global_load_lds_dwordx4 v[2:3], off
	v_lshl_add_u64 v[2:3], s[6:7], 0, v[146:147]
	s_add_i32 m0, s43, 0x1e000
	s_cmpk_lt_u32 s21, 0x100
	global_load_lds_dwordx4 v[2:3], off
	v_lshrrev_b32_e32 v3, 1, v11
	v_and_b32_e32 v3, 24, v3
	v_and_b32_e32 v2, 15, v11
	v_lshlrev_b32_e32 v4, 1, v3
	v_lshl_or_b32 v1, s22, 6, v2
	v_lshl_or_b32 v2, v2, 6, v4
	v_lshlrev_b32_e32 v4, 2, v11
	v_and_b32_e32 v4, 32, v4
	v_bitop3_b32 v5, v2, s18, v4 bitop3:0xde
	v_bitop3_b32 v170, v2, s23, v4 bitop3:0xde
	v_lshlrev_b32_e32 v2, 15, v15
	v_and_b32_e32 v2, 0xffff0000, v2
	v_or_b32_e32 v171, s19, v3
	v_lshl_add_u32 v2, v14, 12, v2
	v_and_b32_e32 v3, 1, v15
	v_lshl_or_b32 v2, v3, 6, v2
	v_lshl_add_u32 v154, v16, 1, v2
	v_lshlrev_b32_e32 v2, 15, v10
	v_and_b32_e32 v2, 0xffff0000, v2
	s_waitcnt vmcnt(6)
	v_lshl_add_u32 v2, v12, 12, v2
	v_and_b32_e32 v3, 1, v10
	s_sext_i32_i8 s69, s20
	s_cselect_b64 s[20:21], -1, 0
	v_lshl_or_b32 v2, v3, 6, v2
	s_add_i32 s66, 0, 0x10000
	s_add_i32 s67, 0, 0x14000
	s_waitcnt lgkmcnt(0)
	s_ashr_i32 s65, s50, 31
	v_mov_b32_e32 v155, v151
	v_lshl_add_u32 v156, v13, 1, v2
	v_mov_b32_e32 v157, v151
	v_mov_b64_e32 v[158:159], 0x200
	v_mov_b64_e32 v[160:161], 0x1ff
	v_add_u32_e32 v172, s66, v170
	v_add_u32_e32 v173, s67, v170
	v_add_u32_e32 v174, 0, v5
	s_barrier
	v_readfirstlane_b32 s101, v0
	s_nop 3
	s_lshr_b32 s101, s101, 8
	s_cmp_eq_u32 s101, 1
	s_cbranch_scc0 .Lsp_2
	s_setprio 1

; #define PG8_STAGE(bufoff, gbase, voff) do { _Pragma("unroll") for (int _i = 0; _i < 2; ++_i) \
;         __builtin_amdgcn_global_load_lds((const unsigned*)((const char*)(gbase) + (voff)[_i]), (PG8_LAS unsigned*)(lds + (bufoff) + ldsw + _i * 8192), 16, 0, 0); } while (0)
; #define PG8_WAIT_V(n) asm volatile("s_waitcnt vmcnt(" #n ")" ::: "memory")
; #define PG8_BAR __builtin_amdgcn_s_barrier()
; template <class Epi, class Sched, bool ALIGN_EPI = false, bool SP2 = false>
; __device__ __forceinline__ void gemm_phase(PG8_LAS unsigned char* lds, const Gemm g, const Sched& S, const Epi& E) {
;     ...
;     const int tid = tid_o, wid = __builtin_amdgcn_readfirstlane(tid >> 6), lane = tid & 63, wr = wid >> 2, wc = wid & 3, fr = lane & 15, fq = lane >> 4;
;     const int K = g.K, nt = K / BK;
;     unsigned voffA[2], voffB[2];
; #pragma unroll
;     for (int i = 0; i < 2; ++i) { int R, C; stage_rc(tid * 16 + i * 8192, R, C); const int Rb = Epi::PERM ? ((R & ~31) + perm32(R & 31)) : R;
;         voffA[i] = (unsigned)(R * g.lda + C) * 2u; voffB[i] = (unsigned)(Rb * g.ldb + C) * 2u; }
;     const size_t kstep = (size_t)(BK * 2);
;     const size_t hA = (size_t)HALF * g.lda * 2, hB = (size_t)HALF * g.ldb * 2;
;     const size_t tA = 2 * hA, tB = 2 * hB, pnA = (size_t)g.a_pn_off * 2;
;     const unsigned ldsw = (unsigned)wid * 1024u;
;     const int aoff = lds_byte(wr * 64 + fr, fq * 8), boff = lds_byte(wc * 32 + fr, fq * 8);
;     ...
;         PG8_STAGE(PG8_SB(1, 0), cB + kstep, voffB); PG8_STAGE(PG8_SA(1, 0), cA + kstep, voffA); PG8_STAGE(PG8_SB(1, 1), cB + hB + kstep, voffB);
;         PG8_WAIT_V(6); PG8_BAR;
.LBB0_953:
	s_add_u32 s16, s6, 0x15800000
	s_addc_u32 s17, s7, 0
	s_add_u32 s20, s6, 0x1e00000
	s_mov_b64 s[22:23], 0x80
	s_addc_u32 s21, s7, 0
	s_and_b32 s67, s9, 3
	s_add_i32 m0, s62, 0x18000
	v_lshl_add_u64 v[8:9], v[8:9], 0, s[22:23]
	s_lshl_b32 s9, s24, 13
	s_lshl_b32 s18, s67, 12
	s_waitcnt vmcnt(2)
	s_barrier
	global_load_lds_dwordx4 v[8:9], off
	v_lshl_add_u64 v[6:7], v[6:7], 0, s[22:23]
	s_add_i32 m0, s62, 0x1a000
	s_add_i32 s69, s62, 0x8000
	s_add_i32 s70, s62, 0xa000
	global_load_lds_dwordx4 v[6:7], off
	v_lshl_add_u64 v[2:3], v[2:3], 0, s[22:23]
	s_mov_b32 m0, s69
	s_add_u32 s6, s50, 0x80080
	global_load_lds_dwordx4 v[2:3], off
	v_lshl_add_u64 v[2:3], v[4:5], 0, s[22:23]
	s_mov_b32 m0, s70
	s_addc_u32 s7, s51, 0
	global_load_lds_dwordx4 v[2:3], off
	s_add_i32 m0, s62, 0x1c000
	v_lshl_add_u64 v[2:3], s[6:7], 0, v[180:181]
	global_load_lds_dwordx4 v[2:3], off
	v_lshl_add_u64 v[2:3], s[6:7], 0, v[184:185]
	s_add_i32 m0, s62, 0x1e000
	s_cmpk_lt_u32 s8, 0x100
	global_load_lds_dwordx4 v[2:3], off
	v_bfe_u32 v3, v10, 4, 2
	v_and_b32_e32 v2, 15, v10
	v_lshlrev_b32_e32 v5, 4, v3
	v_lshl_or_b32 v1, s24, 6, v2
	v_lshl_or_b32 v2, v2, 6, v5
	v_lshlrev_b32_e32 v5, 2, v10
	v_and_b32_e32 v5, 32, v5
	v_bitop3_b32 v6, v2, s9, v5 bitop3:0xde
	v_bitop3_b32 v206, v2, s18, v5 bitop3:0xde
	v_lshlrev_b32_e32 v2, 15, v11
	v_and_b32_e32 v2, 0xffff0000, v2
	v_lshlrev_b32_e32 v4, 3, v3
	v_cmp_eq_u32_e64 s[6:7], 0, v3
	v_lshl_add_u32 v2, v12, 12, v2
	v_and_b32_e32 v3, 1, v11
	v_lshl_or_b32 v2, v3, 6, v2
	v_lshl_add_u32 v186, v13, 1, v2
	v_lshlrev_b32_e32 v2, 15, v14
	v_and_b32_e32 v2, 0xffff0000, v2
	s_waitcnt vmcnt(6)
	v_lshl_add_u32 v2, v15, 12, v2
	v_and_b32_e32 v3, 1, v14
	s_cselect_b64 s[24:25], -1, 0
	v_lshl_or_b32 v2, v3, 6, v2
	s_add_i32 s72, 0, 0x10000
	s_add_i32 s73, 0, 0x14000
	v_lshl_or_b32 v207, s67, 5, v4
	s_waitcnt lgkmcnt(0)
	s_ashr_i32 s71, s66, 31
	v_mov_b32_e32 v187, v181
	v_lshl_add_u32 v188, v16, 1, v2
	v_mov_b32_e32 v189, v181
	v_mov_b64_e32 v[190:191], 0x200
	v_mov_b64_e32 v[192:193], 0x1ff
	v_add_u32_e32 v208, s72, v206
	v_add_u32_e32 v209, s73, v206
	v_add_u32_e32 v210, 0, v6
	v_mbcnt_hi_u32_b32 v211, -1, v222
	s_mov_b32 s74, 0
	s_barrier
	v_readfirstlane_b32 s101, v0
	s_nop 3
	s_lshr_b32 s101, s101, 8
	s_cmp_eq_u32 s101, 1
	s_cbranch_scc0 .Lsp_3
	s_setprio 1

; #define PG8_STAGE(bufoff, gbase, voff) do { _Pragma("unroll") for (int _i = 0; _i < 2; ++_i) \
;         __builtin_amdgcn_global_load_lds((const unsigned*)((const char*)(gbase) + (voff)[_i]), (PG8_LAS unsigned*)(lds + (bufoff) + ldsw + _i * 8192), 16, 0, 0); } while (0)
; #define PG8_WAIT_V(n) asm volatile("s_waitcnt vmcnt(" #n ")" ::: "memory")
; #define PG8_BAR __builtin_amdgcn_s_barrier()
; template <class Epi, class Sched, bool ALIGN_EPI = false, bool SP2 = false>
; __device__ __forceinline__ void gemm_phase(PG8_LAS unsigned char* lds, const Gemm g, const Sched& S, const Epi& E) {
;     ...
;     const int tid = tid_o, wid = __builtin_amdgcn_readfirstlane(tid >> 6), lane = tid & 63, wr = wid >> 2, wc = wid & 3, fr = lane & 15, fq = lane >> 4;
;     const int K = g.K, nt = K / BK;
;     unsigned voffA[2], voffB[2];
; #pragma unroll
;     for (int i = 0; i < 2; ++i) { int R, C; stage_rc(tid * 16 + i * 8192, R, C); const int Rb = Epi::PERM ? ((R & ~31) + perm32(R & 31)) : R;
;         voffA[i] = (unsigned)(R * g.lda + C) * 2u; voffB[i] = (unsigned)(Rb * g.ldb + C) * 2u; }
;     const size_t kstep = (size_t)(BK * 2);
;     const size_t hA = (size_t)HALF * g.lda * 2, hB = (size_t)HALF * g.ldb * 2;
;     const size_t tA = 2 * hA, tB = 2 * hB, pnA = (size_t)g.a_pn_off * 2;
;     const unsigned ldsw = (unsigned)wid * 1024u;
;     const int aoff = lds_byte(wr * 64 + fr, fq * 8), boff = lds_byte(wc * 32 + fr, fq * 8);
;     ...
;         PG8_STAGE(PG8_SB(1, 0), cB + kstep, voffB); PG8_STAGE(PG8_SA(1, 0), cA + kstep, voffA); PG8_STAGE(PG8_SB(1, 1), cB + hB + kstep, voffB);
;         PG8_WAIT_V(6); PG8_BAR;
.LBB0_1042:
	s_add_u32 s16, s6, 0x5800000
	s_addc_u32 s17, s7, 0
	s_lshl_b32 s18, s20, 5
	s_mov_b64 s[20:21], 0x80
	s_and_b32 s18, s18, 0x60
	s_add_i32 m0, s51, 0x18000
	v_lshl_add_u64 v[8:9], v[8:9], 0, s[20:21]
	s_lshl_b32 s1, s24, 13
	s_lshl_b32 s19, s18, 7
	s_waitcnt vmcnt(2)
	s_barrier
	global_load_lds_dwordx4 v[8:9], off
	v_lshl_add_u64 v[6:7], v[6:7], 0, s[20:21]
	s_add_i32 m0, s51, 0x1a000
	s_add_i32 s60, s51, 0x8000
	s_add_i32 s61, s51, 0xa000
	global_load_lds_dwordx4 v[6:7], off
	v_lshl_add_u64 v[2:3], v[2:3], 0, s[20:21]
	s_mov_b32 m0, s60
	s_add_u32 s36, s42, 0x80080
	global_load_lds_dwordx4 v[2:3], off
	v_lshl_add_u64 v[2:3], v[4:5], 0, s[20:21]
	s_mov_b32 m0, s61
	s_addc_u32 s37, s43, 0
	global_load_lds_dwordx4 v[2:3], off
	s_add_i32 m0, s51, 0x1c000
	v_lshl_add_u64 v[2:3], s[36:37], 0, v[134:135]
	global_load_lds_dwordx4 v[2:3], off
	v_lshl_add_u64 v[2:3], s[36:37], 0, v[130:131]
	s_add_i32 m0, s51, 0x1e000
	s_cmpk_lt_u32 s23, 0x100
	global_load_lds_dwordx4 v[2:3], off
	v_lshrrev_b32_e32 v3, 1, v12
	v_and_b32_e32 v4, 24, v3
	v_and_b32_e32 v2, 15, v12
	v_lshlrev_b32_e32 v3, 1, v4
	v_lshl_or_b32 v1, s24, 6, v2
	v_lshl_or_b32 v2, v2, 6, v3
	v_lshlrev_b32_e32 v3, 2, v12
	v_and_b32_e32 v3, 32, v3
	v_bitop3_b32 v5, v2, s1, v3 bitop3:0xde
	v_bitop3_b32 v165, v2, s19, v3 bitop3:0xde
	v_lshlrev_b32_e32 v2, 2, v4
	v_mov_b32_e32 v3, v135
	v_lshl_add_u64 v[2:3], s[6:7], 0, v[2:3]
	s_mov_b64 s[6:7], 0x1e00000
	v_lshl_add_u64 v[138:139], v[2:3], 0, s[6:7]
	v_lshlrev_b32_e32 v2, 15, v15
	v_and_b32_e32 v2, 0xffff0000, v2
	v_lshl_add_u32 v2, v14, 12, v2
	v_and_b32_e32 v3, 1, v15
	v_lshl_or_b32 v2, v3, 6, v2
	v_lshl_add_u32 v140, v16, 1, v2
	v_lshlrev_b32_e32 v2, 15, v10
	v_and_b32_e32 v2, 0xffff0000, v2
	s_waitcnt vmcnt(6)
	v_lshl_add_u32 v2, v11, 12, v2
	v_and_b32_e32 v3, 1, v10
	s_sext_i32_i16 s67, s22
	s_cselect_b64 s[22:23], -1, 0
	v_lshl_or_b32 v2, v3, 6, v2
	s_add_i32 s63, 0, 0x10000
	s_add_i32 s64, 0, 0x14000
	s_waitcnt lgkmcnt(0)
	s_ashr_i32 s62, s58, 31
	v_or_b32_e32 v167, s18, v4
	v_mov_b32_e32 v141, v135
	v_lshl_add_u32 v142, v13, 1, v2
	v_mov_b32_e32 v143, v135
	v_mov_b64_e32 v[144:145], 0xb00
	v_mov_b64_e32 v[146:147], 0xaff
	v_add_u32_e32 v169, s63, v165
	v_add_u32_e32 v171, s64, v165
	v_add_u32_e32 v173, 0, v5
	v_mbcnt_hi_u32_b32 v175, -1, v222
	v_mov_b32_e32 v177, 0x358637bd
	s_mov_b32 s65, 0xf800000
	v_mov_b32_e32 v179, 0x260
	s_movk_i32 s66, 0x2c00
	s_barrier
	s_mov_b32 s98, -1
	v_readfirstlane_b32 s101, v0
	s_nop 3
	s_lshr_b32 s101, s101, 8
	s_cmp_eq_u32 s101, 1
	s_cbranch_scc0 .Lsp_4
	s_setprio 1

; #define PG8_STAGE(bufoff, gbase, voff) do { _Pragma("unroll") for (int _i = 0; _i < 2; ++_i) \
;         __builtin_amdgcn_global_load_lds((const unsigned*)((const char*)(gbase) + (voff)[_i]), (PG8_LAS unsigned*)(lds + (bufoff) + ldsw + _i * 8192), 16, 0, 0); } while (0)
; #define PG8_WAIT_V(n) asm volatile("s_waitcnt vmcnt(" #n ")" ::: "memory")
; #define PG8_BAR __builtin_amdgcn_s_barrier()
; template <class Epi, class Sched, bool ALIGN_EPI = false, bool SP2 = false>
; __device__ __forceinline__ void gemm_phase(PG8_LAS unsigned char* lds, const Gemm g, const Sched& S, const Epi& E) {
;     ...
;     const int tid = tid_o, wid = __builtin_amdgcn_readfirstlane(tid >> 6), lane = tid & 63, wr = wid >> 2, wc = wid & 3, fr = lane & 15, fq = lane >> 4;
;     const int K = g.K, nt = K / BK;
;     unsigned voffA[2], voffB[2];
; #pragma unroll
;     for (int i = 0; i < 2; ++i) { int R, C; stage_rc(tid * 16 + i * 8192, R, C); const int Rb = Epi::PERM ? ((R & ~31) + perm32(R & 31)) : R;
;         voffA[i] = (unsigned)(R * g.lda + C) * 2u; voffB[i] = (unsigned)(Rb * g.ldb + C) * 2u; }
;     const size_t kstep = (size_t)(BK * 2);
;     const size_t hA = (size_t)HALF * g.lda * 2, hB = (size_t)HALF * g.ldb * 2;
;     const size_t tA = 2 * hA, tB = 2 * hB, pnA = (size_t)g.a_pn_off * 2;
;     const unsigned ldsw = (unsigned)wid * 1024u;
;     const int aoff = lds_byte(wr * 64 + fr, fq * 8), boff = lds_byte(wc * 32 + fr, fq * 8);
;     ...
;         PG8_STAGE(PG8_SB(1, 0), cB + kstep, voffB); PG8_STAGE(PG8_SA(1, 0), cA + kstep, voffA); PG8_STAGE(PG8_SB(1, 1), cB + hB + kstep, voffB);
;         PG8_WAIT_V(6); PG8_BAR;
.LBB0_1113:
	s_add_u32 s12, s6, 0x15800000
	s_addc_u32 s13, s7, 0
	s_add_u32 s14, s6, 0x2000000
	s_mov_b64 s[16:17], 0x80
	s_addc_u32 s15, s7, 0
	s_and_b32 s51, s4, 3
	s_add_i32 m0, s46, 0x18000
	v_lshl_add_u64 v[8:9], v[8:9], 0, s[16:17]
	s_lshl_b32 s4, s5, 13
	s_lshl_b32 s18, s51, 12
	s_waitcnt vmcnt(2)
	s_barrier
	global_load_lds_dwordx4 v[8:9], off
	v_lshl_add_u64 v[4:5], v[4:5], 0, s[16:17]
	s_add_i32 m0, s46, 0x1a000
	s_add_i32 s52, s46, 0x8000
	s_add_i32 s53, s46, 0xa000
	global_load_lds_dwordx4 v[4:5], off
	v_lshl_add_u64 v[2:3], v[2:3], 0, s[16:17]
	s_mov_b32 m0, s52
	s_add_u32 s6, s36, 0x160080
	global_load_lds_dwordx4 v[2:3], off
	v_lshl_add_u64 v[2:3], v[6:7], 0, s[16:17]
	s_mov_b32 m0, s53
	s_addc_u32 s7, s37, 0
	global_load_lds_dwordx4 v[2:3], off
	s_add_i32 m0, s46, 0x1c000
	v_lshl_add_u64 v[2:3], s[6:7], 0, v[156:157]
	global_load_lds_dwordx4 v[2:3], off
	v_lshl_add_u64 v[2:3], s[6:7], 0, v[160:161]
	s_add_i32 m0, s46, 0x1e000
	s_mov_b64 s[6:7], 0x160080
	global_load_lds_dwordx4 v[2:3], off
	v_bfe_u32 v3, v10, 4, 2
	v_and_b32_e32 v2, 15, v10
	v_lshlrev_b32_e32 v5, 4, v3
	v_lshl_or_b32 v1, s5, 6, v2
	v_lshl_or_b32 v2, v2, 6, v5
	v_lshlrev_b32_e32 v5, 2, v10
	v_and_b32_e32 v5, 32, v5
	v_lshlrev_b32_e32 v4, 3, v3
	v_bitop3_b32 v6, v2, s4, v5 bitop3:0xde
	v_bitop3_b32 v188, v2, s18, v5 bitop3:0xde
	v_cmp_eq_u32_e64 s[4:5], 0, v3
	v_lshrrev_b32_e32 v3, 1, v11
	v_mul_lo_u32 v2, v12, s9
	v_mad_u64_u32 v[2:3], s[38:39], v3, s22, v[2:3]
	v_or_b32_e32 v2, v2, v13
	v_add_lshl_u32 v2, v2, v14, 1
	v_mov_b32_e32 v3, v157
	v_lshl_add_u64 v[162:163], v[2:3], 0, s[6:7]
	v_lshrrev_b32_e32 v3, 1, v15
	v_mul_lo_u32 v2, v16, s9
	s_cmpk_lt_u32 s8, 0x100
	v_mad_u64_u32 v[2:3], s[8:9], v3, s22, v[2:3]
	s_waitcnt vmcnt(6)
	v_or_b32_e32 v2, v2, v17
	s_cselect_b64 s[20:21], -1, 0
	v_add_lshl_u32 v2, v2, v18, 1
	v_mov_b32_e32 v3, v157
	s_add_i32 s55, 0, 0x10000
	s_add_i32 s56, 0, 0x14000
	v_lshl_or_b32 v189, s51, 5, v4
	s_waitcnt lgkmcnt(0)
	s_ashr_i32 s54, s50, 31
	v_lshl_add_u64 v[164:165], v[2:3], 0, s[6:7]
	v_mov_b64_e32 v[166:167], 0x200
	v_mov_b64_e32 v[168:169], 0x1ff
	v_add_u32_e32 v190, s55, v188
	v_add_u32_e32 v191, s56, v188
	v_add_u32_e32 v192, 0, v6
	v_mbcnt_hi_u32_b32 v193, -1, v222
	s_mov_b32 s57, 0
	s_barrier
	v_readfirstlane_b32 s101, v0
	s_nop 3
	s_lshr_b32 s101, s101, 8
	s_cmp_eq_u32 s101, 1
	s_cbranch_scc0 .Lsp_5
	s_setprio 1
